# v076 plus ret_unit_c: third load batch issued with the second (one load round trip less per unit)
# baseline (speedup 1.0000x reference)
; __device__ __forceinline__ unsigned cvt_pk_bf16(float lo, float hi) { const f32x2_t v = {lo, hi}; const bf16x2_t b = __builtin_convertvector(v, bf16x2_t); return __builtin_bit_cast(unsigned, b); }
; #define LAS __attribute__((address_space(3)))
; __device__ __forceinline__ float lo_bf(unsigned x) { return __uint_as_float(x << 16); }
; __device__ __forceinline__ float hi_bf(unsigned x) { return __uint_as_float(x & 0xffff0000u); }
; template <bool WITH_K>
; __device__ __forceinline__ void ret_load_qk(PR P, LAS bf16_t* QP, LAS bf16_t* KB, unsigned (&kth)[4][4], const int tidv, const int row0, const int n, const int h, const float kd0, const float g32) {
;     const bf16_t* PS = (const bf16_t*)(P.ws + WS_BIG); const float* rc = (const float*)(P.ws + WS_ROPE); const float* rs = rc + 2052 * 64;
;     float kd = kd0;
; #pragma unroll
;     for (int it = 0; it < 4; ++it) { const int idx = it * 512 + tidv, i = idx >> 4, f = (idx & 15) * 4;
;         const bf16_t* src = PS + (size_t)(row0 + i) * NCOLS + 1792 + h * 128;
;         const u32x2 q1 = *(const u32x2*)(src + f), q2 = *(const u32x2*)(src + 64 + f);
;         u32x2 k1 = (u32x2){0u, 0u}, k2 = k1; if (WITH_K) { k1 = *(const u32x2*)(src + 512 + f); k2 = *(const u32x2*)(src + 576 + f); }
;         const float4 cs = *(const float4*)(rc + (size_t)(n * 128 + i) * 64 + f), sn = *(const float4*)(rs + (size_t)(n * 128 + i) * 64 + f);
;         const float c4[4] = {cs.x, cs.y, cs.z, cs.w}, s4[4] = {sn.x, sn.y, sn.z, sn.w};
;         const float qa[4] = {lo_bf(q1.x), hi_bf(q1.x), lo_bf(q1.y), hi_bf(q1.y)}, qb[4] = {lo_bf(q2.x), hi_bf(q2.x), lo_bf(q2.y), hi_bf(q2.y)};
;         float qo1[4], qo2[4];
; #pragma unroll
;         for (int x = 0; x < 4; ++x) { qo1[x] = qa[x] * c4[x] - qb[x] * s4[x]; qo2[x] = qa[x] * s4[x] + qb[x] * c4[x]; }
;         u32x2 w; w.x = pg8::cvt_pk_bf16(qo1[0], qo1[1]); w.y = pg8::cvt_pk_bf16(qo1[2], qo1[3]); *(LAS u32x2*)(QP + i * RS + f) = w;
;         w.x = pg8::cvt_pk_bf16(qo2[0], qo2[1]); w.y = pg8::cvt_pk_bf16(qo2[2], qo2[3]); *(LAS u32x2*)(QP + i * RS + 64 + f) = w;
; __device__ __forceinline__ void ret_unit_c(PR P, LAS unsigned char* lds, const int bh, const int n, const int wv) {
;     ...
; #pragma unroll
;     for (int it = 0; it < 4; ++it) { const int idx = it * 512 + tid, e = idx >> 4, d8 = (idx & 15) * 8;
;         *(LAS u32x4*)(ST + e * RS + d8) = *(const u32x4*)(KVB + e * 128 + d8); }
.LBB0_654:
	s_add_i32 s18, s2, s28
	s_ashr_i32 s18, s18, 4
	s_and_b32 s44, s18, 3
	s_sub_i32 s26, s18, 29
	s_ashr_i32 s27, s18, 31
	s_cmp_lt_i32 s18, 29
	s_cselect_b32 s45, s29, 0x1444800
	s_cselect_b32 s27, s27, 0
	s_cselect_b32 s26, s18, s26
	s_add_u32 s45, s10, s45
	s_addc_u32 s46, s11, 0
	s_lshl_b64 s[26:27], s[26:27], 19
	s_add_u32 s26, s45, s26
	s_addc_u32 s27, s46, s27
	v_cvt_f32_ubyte0_e32 v0, s44
	s_add_u32 s26, s26, s7
	v_sub_f32_e32 v34, 0xc0a00000, v0
	s_addc_u32 s27, s27, 0
	v_cmp_gt_f32_e32 vcc, s30, v34
	s_and_b64 s[46:47], vcc, exec
	s_cselect_b32 s55, 0xffffffc0, 0
	s_lshl_b32 s18, s18, 9
	v_mbcnt_lo_u32_b32 v2, -1, 0
	v_mbcnt_hi_u32_b32 v2, -1, v2
	s_and_b32 s18, s18, 0xfffff800
	v_add_u32_e32 v3, s33, v2
	s_or_b32 s45, s18, s6
	v_lshlrev_b32_e32 v0, 2, v2
	v_ashrrev_i32_e32 v46, 4, v3
	v_and_b32_e32 v6, 60, v0
	v_add_u32_e32 v4, s45, v46
	v_lshlrev_b32_e32 v28, 2, v6
	v_mad_i64_i32 v[4:5], s[46:47], v4, s31, v[30:31]
	s_lshl_b32 s18, s44, 8
	v_lshl_add_u64 v[0:1], s[14:15], 0, v[28:29]
	v_lshl_add_u64 v[20:21], s[16:17], 0, v[28:29]
	v_lshl_add_u64 v[4:5], v[4:5], 0, s[18:19]
	v_lshlrev_b32_e32 v28, 1, v6
	v_lshl_add_u64 v[4:5], v[4:5], 0, v[28:29]
	v_cndmask_b32_e32 v35, 0, v62, vcc
	v_lshl_add_u64 v[6:7], v[4:5], 0, s[20:21]
	v_add_co_u32_e32 v4, vcc, s34, v4
	v_add_f32_e32 v34, v34, v35
	s_nop 0
	v_addc_co_u32_e32 v5, vcc, 0, v5, vcc
	global_load_dwordx2 v[22:23], v[4:5], off offset:1536
	global_load_dwordx2 v[24:25], v[6:7], off offset:128
	v_add_u32_e32 v4, s6, v46
	v_ashrrev_i32_e32 v5, 31, v4
	v_lshlrev_b64 v[8:9], 8, v[4:5]
	v_add_u32_e32 v4, 0x200, v3
	v_ashrrev_i32_e32 v47, 4, v4
	v_add_u32_e32 v4, s45, v47
	v_mad_i64_i32 v[4:5], s[46:47], v4, s31, v[30:31]
	v_lshl_add_u64 v[4:5], v[4:5], 0, s[18:19]
	v_lshl_add_u64 v[12:13], v[4:5], 0, v[28:29]
	v_add_co_u32_e32 v4, vcc, s34, v12
	v_exp_f32_e32 v34, v34
	s_nop 0
	v_addc_co_u32_e32 v5, vcc, 0, v13, vcc
	v_lshl_add_u64 v[12:13], v[12:13], 0, s[20:21]
	global_load_dwordx2 v[26:27], v[4:5], off offset:1536
	global_load_dwordx2 v[32:33], v[12:13], off offset:128
	v_lshl_add_u64 v[4:5], v[20:21], 0, v[8:9]
	global_load_dwordx4 v[4:7], v[4:5], off
	v_lshl_add_u64 v[8:9], v[0:1], 0, v[8:9]
	v_add_u32_e32 v12, s6, v47
	global_load_dwordx4 v[8:11], v[8:9], off
	v_ashrrev_i32_e32 v13, 31, v12
	v_lshlrev_b64 v[12:13], 8, v[12:13]
	v_lshl_add_u64 v[16:17], v[0:1], 0, v[12:13]
	v_lshl_add_u64 v[12:13], v[20:21], 0, v[12:13]
	global_load_dwordx4 v[12:15], v[12:13], off
	s_nop 0
	global_load_dwordx4 v[16:19], v[16:17], off
	v_ldexp_f32 v34, v34, s55
	v_sub_f32_e32 v57, 1.0, v34
	v_mul_lo_u32 v48, v46, s35
	v_add3_u32 v44, 0, v48, v28
	v_mul_lo_u32 v49, v47, s35
	v_bfe_u32 v56, v3, 6, 1
	s_waitcnt vmcnt(7)
	v_lshlrev_b32_e32 v34, 16, v22
	v_and_b32_e32 v35, 0xffff0000, v22
	s_waitcnt vmcnt(6)
	v_lshlrev_b32_e32 v36, 16, v24
	v_and_b32_e32 v37, 0xffff0000, v24
	v_lshlrev_b32_e32 v22, 16, v23
	v_and_b32_e32 v23, 0xffff0000, v23
	v_lshlrev_b32_e32 v24, 16, v25
	v_and_b32_e32 v25, 0xffff0000, v25
	s_waitcnt vmcnt(5)
	v_lshlrev_b32_e32 v38, 16, v26
	v_and_b32_e32 v39, 0xffff0000, v26
	s_waitcnt vmcnt(3)
	v_pk_mul_f32 v[40:41], v[4:5], v[34:35]
	v_pk_mul_f32 v[4:5], v[4:5], v[36:37]
	v_pk_mul_f32 v[42:43], v[6:7], v[22:23]
	v_pk_mul_f32 v[6:7], v[6:7], v[24:25]
	s_waitcnt vmcnt(2)
	v_pk_fma_f32 v[36:37], v[8:9], v[36:37], v[40:41]
	v_pk_fma_f32 v[4:5], v[8:9], v[34:35], v[4:5] neg_lo:[0,0,1] neg_hi:[0,0,1]
	v_pk_fma_f32 v[8:9], v[10:11], v[24:25], v[42:43]
	v_pk_fma_f32 v[6:7], v[10:11], v[22:23], v[6:7] neg_lo:[0,0,1] neg_hi:[0,0,1]
	v_cvt_pk_bf16_f32 v4, v4, v5
	v_cvt_pk_bf16_f32 v5, v6, v7
	v_cvt_pk_bf16_f32 v6, v36, v37
	v_cvt_pk_bf16_f32 v7, v8, v9
	ds_write2_b64 v44, v[4:5], v[6:7] offset1:16
	v_lshlrev_b32_e32 v4, 16, v32
	v_and_b32_e32 v5, 0xffff0000, v32
	s_waitcnt vmcnt(1)
	v_pk_mul_f32 v[6:7], v[12:13], v[38:39]
	v_lshlrev_b32_e32 v8, 16, v27
	v_and_b32_e32 v9, 0xffff0000, v27
	s_waitcnt vmcnt(0)
	v_pk_fma_f32 v[6:7], v[16:17], v[4:5], v[6:7]
	v_pk_mul_f32 v[4:5], v[12:13], v[4:5]
	v_lshlrev_b32_e32 v10, 16, v33
	v_and_b32_e32 v11, 0xffff0000, v33
	v_pk_mul_f32 v[12:13], v[14:15], v[8:9]
	v_pk_fma_f32 v[4:5], v[16:17], v[38:39], v[4:5] neg_lo:[0,0,1] neg_hi:[0,0,1]
	v_pk_fma_f32 v[12:13], v[18:19], v[10:11], v[12:13]
	v_pk_mul_f32 v[10:11], v[14:15], v[10:11]
	v_cvt_pk_bf16_f32 v4, v4, v5
	v_pk_fma_f32 v[8:9], v[18:19], v[8:9], v[10:11] neg_lo:[0,0,1] neg_hi:[0,0,1]
	v_cvt_pk_bf16_f32 v6, v6, v7
	v_cvt_pk_bf16_f32 v5, v8, v9
	v_add3_u32 v8, 0, v49, v28
	v_cvt_pk_bf16_f32 v7, v12, v13
	ds_write2_b64 v8, v[4:5], v[6:7] offset1:16
	v_add_u32_e32 v4, 0x400, v3
	v_ashrrev_i32_e32 v50, 4, v4
	v_add_u32_e32 v4, s45, v50
	v_mad_i64_i32 v[4:5], s[46:47], v4, s31, v[30:31]
	v_lshl_add_u64 v[4:5], v[4:5], 0, s[18:19]
	v_lshl_add_u64 v[4:5], v[4:5], 0, v[28:29]
	v_lshl_add_u64 v[6:7], v[4:5], 0, s[20:21]
	v_add_co_u32_e32 v4, vcc, s34, v4
	v_mul_lo_u32 v52, v50, s35
	s_nop 0
	v_addc_co_u32_e32 v5, vcc, 0, v5, vcc
	global_load_dwordx2 v[22:23], v[4:5], off offset:1536
	global_load_dwordx2 v[24:25], v[6:7], off offset:128
	v_add_u32_e32 v4, 0x600, v3
	v_ashrrev_i32_e32 v51, 4, v4
	v_add_u32_e32 v4, s45, v51
	v_mad_i64_i32 v[4:5], s[46:47], v4, s31, v[30:31]
	v_lshl_add_u64 v[4:5], v[4:5], 0, s[18:19]
	v_lshl_add_u64 v[4:5], v[4:5], 0, v[28:29]
	v_add_co_u32_e32 v6, vcc, s34, v4
	v_add_u32_e32 v8, s6, v51
	s_nop 0
	v_addc_co_u32_e32 v7, vcc, 0, v5, vcc
	v_lshl_add_u64 v[4:5], v[4:5], 0, s[20:21]
	global_load_dwordx2 v[26:27], v[6:7], off offset:1536
	global_load_dwordx2 v[32:33], v[4:5], off offset:128
	v_add_u32_e32 v4, s6, v50
	v_ashrrev_i32_e32 v5, 31, v4
	v_lshlrev_b64 v[12:13], 8, v[4:5]
	v_ashrrev_i32_e32 v9, 31, v8
	v_lshl_add_u64 v[4:5], v[20:21], 0, v[12:13]
	v_lshlrev_b64 v[16:17], 8, v[8:9]
	global_load_dwordx4 v[4:7], v[4:5], off
	v_lshl_add_u64 v[8:9], v[20:21], 0, v[16:17]
	v_lshl_add_u64 v[12:13], v[0:1], 0, v[12:13]
	global_load_dwordx4 v[8:11], v[8:9], off
	v_lshl_add_u64 v[0:1], v[0:1], 0, v[16:17]
	global_load_dwordx4 v[12:15], v[12:13], off
	v_mul_lo_u32 v53, v51, s35
	global_load_dwordx4 v[16:19], v[0:1], off
	v_lshlrev_b32_e32 v216, 4, v2
	v_and_b32_e32 v216, 0xf0, v216
	v_mov_b32_e32 v217, 0
	v_lshl_add_u64 v[218:219], s[26:27], 0, v[216:217]
	v_lshlrev_b32_e32 v220, 7, v46
	v_ashrrev_i32_e32 v221, 31, v220
	v_lshl_add_u64 v[220:221], v[220:221], 1, v[218:219]
	v_lshlrev_b32_e32 v222, 7, v47
	v_ashrrev_i32_e32 v223, 31, v222
	v_lshl_add_u64 v[222:223], v[222:223], 1, v[218:219]
	v_lshlrev_b32_e32 v224, 7, v50
	v_ashrrev_i32_e32 v225, 31, v224
	v_lshl_add_u64 v[224:225], v[224:225], 1, v[218:219]
	v_lshlrev_b32_e32 v226, 7, v51
	v_ashrrev_i32_e32 v227, 31, v226
	v_lshl_add_u64 v[226:227], v[226:227], 1, v[218:219]
	global_load_dwordx4 v[200:203], v[220:221], off
	global_load_dwordx4 v[204:207], v[222:223], off
	global_load_dwordx4 v[208:211], v[224:225], off
	global_load_dwordx4 v[212:215], v[226:227], off
	v_add3_u32 v54, 0, v52, v28
	v_add3_u32 v28, 0, v53, v28
	s_waitcnt vmcnt(11)
; __device__ __forceinline__ unsigned cvt_pk_bf16(float lo, float hi) { const f32x2_t v = {lo, hi}; const bf16x2_t b = __builtin_convertvector(v, bf16x2_t); return __builtin_bit_cast(unsigned, b); }
; #define LAS __attribute__((address_space(3)))
; __device__ __forceinline__ float lo_bf(unsigned x) { return __uint_as_float(x << 16); }
; template <bool WITH_K>
; __device__ __forceinline__ void ret_load_qk(PR P, LAS bf16_t* QP, LAS bf16_t* KB, unsigned (&kth)[4][4], const int tidv, const int row0, const int n, const int h, const float kd0, const float g32) {
;     ...
;         const float c4[4] = {cs.x, cs.y, cs.z, cs.w}, s4[4] = {sn.x, sn.y, sn.z, sn.w};
;         const float qa[4] = {lo_bf(q1.x), hi_bf(q1.x), lo_bf(q1.y), hi_bf(q1.y)}, qb[4] = {lo_bf(q2.x), hi_bf(q2.x), lo_bf(q2.y), hi_bf(q2.y)};
;         float qo1[4], qo2[4];
; #pragma unroll
;         for (int x = 0; x < 4; ++x) { qo1[x] = qa[x] * c4[x] - qb[x] * s4[x]; qo2[x] = qa[x] * s4[x] + qb[x] * c4[x]; }
;         u32x2 w; w.x = pg8::cvt_pk_bf16(qo1[0], qo1[1]); w.y = pg8::cvt_pk_bf16(qo1[2], qo1[3]); *(LAS u32x2*)(QP + i * RS + f) = w;
;         w.x = pg8::cvt_pk_bf16(qo2[0], qo2[1]); w.y = pg8::cvt_pk_bf16(qo2[2], qo2[3]); *(LAS u32x2*)(QP + i * RS + 64 + f) = w;
; __device__ __forceinline__ void ret_unit_c(PR P, LAS unsigned char* lds, const int bh, const int n, const int wv) {
;     ...
; #pragma unroll
;     for (int it = 0; it < 4; ++it) { const int idx = it * 512 + tid, e = idx >> 4, d8 = (idx & 15) * 8;
;         *(LAS u32x4*)(ST + e * RS + d8) = *(const u32x4*)(KVB + e * 128 + d8); }
;     __syncthreads();
;     f32x4 accY[2][4];
; #pragma unroll
;     for (int mt = 0; mt < 2; ++mt)
; #pragma unroll
;         for (int nt = 0; nt < 4; ++nt) accY[mt][nt] = (f32x4){0.f, 0.f, 0.f, 0.f};
; #pragma unroll
;     for (int ks = 0; ks < 4; ++ks) { bf16x8 aq[2];
; #pragma unroll
;         for (int mt = 0; mt < 2; ++mt) aq[mt] = *(const LAS bf16x8*)(QP + (wr * 32 + mt * 16 + fr) * RS + ks * 32 + fq * 8);
; #pragma unroll
;         for (int nt = 0; nt < 4; ++nt) { const bf16x8 bs = *(const LAS bf16x8*)(ST + (wc * 64 + nt * 16 + fr) * RS + ks * 32 + fq * 8);
; #pragma unroll
;             for (int mt = 0; mt < 2; ++mt) accY[mt][nt] = __builtin_amdgcn_mfma_f32_16x16x32_bf16(aq[mt], bs, accY[mt][nt], 0, 0, 0); }
;         __builtin_amdgcn_sched_barrier(0); }
	v_lshlrev_b32_e32 v0, 16, v22
	v_and_b32_e32 v1, 0xffff0000, v22
	s_waitcnt vmcnt(10)
	v_lshlrev_b32_e32 v20, 16, v24
	v_and_b32_e32 v21, 0xffff0000, v24
	v_lshlrev_b32_e32 v22, 16, v23
	v_and_b32_e32 v23, 0xffff0000, v23
	v_lshlrev_b32_e32 v24, 16, v25
	v_and_b32_e32 v25, 0xffff0000, v25
	s_waitcnt vmcnt(9)
	v_lshlrev_b32_e32 v34, 16, v26
	v_and_b32_e32 v35, 0xffff0000, v26
	s_waitcnt vmcnt(8)
	v_lshlrev_b32_e32 v36, 16, v32
	v_and_b32_e32 v37, 0xffff0000, v32
	v_lshlrev_b32_e32 v26, 16, v27
	v_and_b32_e32 v27, 0xffff0000, v27
	v_lshlrev_b32_e32 v32, 16, v33
	v_and_b32_e32 v33, 0xffff0000, v33
	s_waitcnt vmcnt(7)
	v_pk_mul_f32 v[38:39], v[4:5], v[0:1]
	v_pk_mul_f32 v[4:5], v[4:5], v[20:21]
	v_pk_mul_f32 v[40:41], v[6:7], v[22:23]
	v_pk_mul_f32 v[6:7], v[6:7], v[24:25]
	s_waitcnt vmcnt(6)
	v_pk_mul_f32 v[42:43], v[8:9], v[34:35]
	v_pk_mul_f32 v[8:9], v[8:9], v[36:37]
	v_pk_mul_f32 v[44:45], v[10:11], v[26:27]
	v_pk_mul_f32 v[10:11], v[10:11], v[32:33]
	s_waitcnt vmcnt(5)
	v_pk_fma_f32 v[20:21], v[12:13], v[20:21], v[38:39]
	v_pk_fma_f32 v[0:1], v[12:13], v[0:1], v[4:5] neg_lo:[0,0,1] neg_hi:[0,0,1]
	v_pk_fma_f32 v[4:5], v[14:15], v[24:25], v[40:41]
	v_pk_fma_f32 v[6:7], v[14:15], v[22:23], v[6:7] neg_lo:[0,0,1] neg_hi:[0,0,1]
	s_waitcnt vmcnt(4)
	v_pk_fma_f32 v[12:13], v[16:17], v[36:37], v[42:43]
	v_pk_fma_f32 v[8:9], v[16:17], v[34:35], v[8:9] neg_lo:[0,0,1] neg_hi:[0,0,1]
	v_pk_fma_f32 v[14:15], v[18:19], v[32:33], v[44:45]
	v_pk_fma_f32 v[10:11], v[18:19], v[26:27], v[10:11] neg_lo:[0,0,1] neg_hi:[0,0,1]
	v_cvt_pk_bf16_f32 v0, v0, v1
	v_cvt_pk_bf16_f32 v1, v6, v7
	v_cvt_pk_bf16_f32 v6, v20, v21
	v_cvt_pk_bf16_f32 v7, v4, v5
	v_cvt_pk_bf16_f32 v4, v8, v9
	v_cvt_pk_bf16_f32 v5, v10, v11
	v_cvt_pk_bf16_f32 v8, v12, v13
	v_cvt_pk_bf16_f32 v9, v14, v15
	ds_write2_b64 v54, v[0:1], v[6:7] offset1:16
	ds_write2_b64 v28, v[4:5], v[8:9] offset1:16
	v_lshlrev_b32_e32 v0, 4, v2
	v_and_b32_e32 v28, 0xf0, v0
	v_ashrrev_i32_e32 v66, 2, v3
	v_and_b32_e32 v1, 15, v2
	v_and_b32_e32 v3, 0xffffffe0, v66
	v_bfe_u32 v0, v2, 4, 2
	v_or_b32_e32 v23, v3, v1
	v_lshlrev_b32_e32 v20, 4, v0
	v_add_u32_e32 v22, s36, v28
	v_mul_lo_u32 v23, v23, s35
	v_add_u32_e32 v24, v22, v48
	v_add3_u32 v28, 0, v20, v23
	v_add_u32_e32 v25, v22, v49
	v_add_u32_e32 v26, v22, v52
	v_add_u32_e32 v22, v22, v53
	v_lshl_or_b32 v21, v56, 6, v1
	s_waitcnt vmcnt(3)
	ds_write_b128 v24, v[200:203]
	s_waitcnt vmcnt(2)
	ds_write_b128 v25, v[204:207]
	s_waitcnt vmcnt(1)
	ds_write_b128 v26, v[208:211]
	s_waitcnt vmcnt(0)
	ds_write_b128 v22, v[212:215]
	s_waitcnt lgkmcnt(0)
	s_barrier
	ds_read_b128 v[4:7], v28
	v_mul_u32_u24_e32 v8, 0x110, v21
	v_add3_u32 v58, s36, v20, v8
	ds_read_b128 v[8:11], v28 offset:4352
	ds_read_b128 v[12:15], v58
	ds_read_b128 v[16:19], v58 offset:4352
	ds_read_b128 v[32:35], v58 offset:8704
	ds_read_b128 v[36:39], v58 offset:13056
	s_waitcnt lgkmcnt(3)
	v_mfma_f32_16x16x32_bf16 v[20:23], v[4:7], v[12:15], 0
	v_mfma_f32_16x16x32_bf16 v[12:15], v[8:11], v[12:15], 0
	s_waitcnt lgkmcnt(2)
	v_mfma_f32_16x16x32_bf16 v[24:27], v[4:7], v[16:19], 0
	v_mfma_f32_16x16x32_bf16 v[16:19], v[8:11], v[16:19], 0
	s_waitcnt lgkmcnt(1)
	v_mfma_f32_16x16x32_bf16 v[40:43], v[4:7], v[32:35], 0
	v_mfma_f32_16x16x32_bf16 v[32:35], v[8:11], v[32:35], 0
	s_waitcnt lgkmcnt(0)
	v_mfma_f32_16x16x32_bf16 v[4:7], v[4:7], v[36:39], 0
	v_mfma_f32_16x16x32_bf16 v[8:11], v[8:11], v[36:39], 0
	ds_read_b128 v[36:39], v28 offset:64
	ds_read_b128 v[44:47], v28 offset:4416
	ds_read_b128 v[48:51], v58 offset:64
	ds_read_b128 v[52:55], v58 offset:4416
	s_waitcnt lgkmcnt(1)
	v_mfma_f32_16x16x32_bf16 v[20:23], v[36:39], v[48:51], v[20:23]
	v_mfma_f32_16x16x32_bf16 v[12:15], v[44:47], v[48:51], v[12:15]
	s_waitcnt lgkmcnt(0)
	v_mfma_f32_16x16x32_bf16 v[24:27], v[36:39], v[52:55], v[24:27]
	v_mfma_f32_16x16x32_bf16 v[16:19], v[44:47], v[52:55], v[16:19]
	ds_read_b128 v[48:51], v58 offset:8768
	ds_read_b128 v[52:55], v58 offset:13120
	s_waitcnt lgkmcnt(1)
	v_mfma_f32_16x16x32_bf16 v[40:43], v[36:39], v[48:51], v[40:43]
	v_mfma_f32_16x16x32_bf16 v[32:35], v[44:47], v[48:51], v[32:35]
	s_waitcnt lgkmcnt(0)
	v_mfma_f32_16x16x32_bf16 v[4:7], v[36:39], v[52:55], v[4:7]
	v_mfma_f32_16x16x32_bf16 v[8:11], v[44:47], v[52:55], v[8:11]
	ds_read_b128 v[36:39], v28 offset:128
	ds_read_b128 v[44:47], v28 offset:4480
	ds_read_b128 v[48:51], v58 offset:128
	ds_read_b128 v[52:55], v58 offset:4480
	s_waitcnt lgkmcnt(1)
	v_mfma_f32_16x16x32_bf16 v[20:23], v[36:39], v[48:51], v[20:23]
	v_mfma_f32_16x16x32_bf16 v[12:15], v[44:47], v[48:51], v[12:15]
	s_waitcnt lgkmcnt(0)
	v_mfma_f32_16x16x32_bf16 v[24:27], v[36:39], v[52:55], v[24:27]
	v_mfma_f32_16x16x32_bf16 v[16:19], v[44:47], v[52:55], v[16:19]
	ds_read_b128 v[48:51], v58 offset:8832
	ds_read_b128 v[52:55], v58 offset:13184
	s_waitcnt lgkmcnt(1)
	v_mfma_f32_16x16x32_bf16 v[40:43], v[36:39], v[48:51], v[40:43]
	v_mfma_f32_16x16x32_bf16 v[32:35], v[44:47], v[48:51], v[32:35]
	s_waitcnt lgkmcnt(0)
	v_mfma_f32_16x16x32_bf16 v[4:7], v[36:39], v[52:55], v[4:7]
	v_mfma_f32_16x16x32_bf16 v[8:11], v[44:47], v[52:55], v[8:11]
	ds_read_b128 v[36:39], v28 offset:192
	ds_read_b128 v[44:47], v28 offset:4544
	ds_read_b128 v[48:51], v58 offset:192
	ds_read_b128 v[52:55], v58 offset:4544
	s_waitcnt lgkmcnt(1)
	v_mfma_f32_16x16x32_bf16 v[20:23], v[36:39], v[48:51], v[20:23]
	v_mfma_f32_16x16x32_bf16 v[12:15], v[44:47], v[48:51], v[12:15]
	s_waitcnt lgkmcnt(0)
	v_mfma_f32_16x16x32_bf16 v[24:27], v[36:39], v[52:55], v[24:27]
	v_mfma_f32_16x16x32_bf16 v[16:19], v[44:47], v[52:55], v[16:19]
	ds_read_b128 v[48:51], v58 offset:8896
	ds_read_b128 v[52:55], v58 offset:13248
	s_waitcnt lgkmcnt(1)
; #define LAS __attribute__((address_space(3)))
; __device__ __forceinline__ void ret_unit_c(PR P, LAS unsigned char* lds, const int bh, const int n, const int wv) {
;     ...
;     const float lg2 = log2f(1.0f - exp2f(-5.0f - (float)h));
;     ...
;     for (int ks = 0; ks < 4; ++ks) { bf16x8 aq[2];
; #pragma unroll
;         for (int mt = 0; mt < 2; ++mt) aq[mt] = *(const LAS bf16x8*)(QP + (wr * 32 + mt * 16 + fr) * RS + ks * 32 + fq * 8);
; #pragma unroll
;         for (int nt = 0; nt < 4; ++nt) { const bf16x8 bs = *(const LAS bf16x8*)(ST + (wc * 64 + nt * 16 + fr) * RS + ks * 32 + fq * 8);
; #pragma unroll
;             for (int mt = 0; mt < 2; ++mt) accY[mt][nt] = __builtin_amdgcn_mfma_f32_16x16x32_bf16(aq[mt], bs, accY[mt][nt], 0, 0, 0); }
;         __builtin_amdgcn_sched_barrier(0); }
; #pragma unroll
;     for (int mt = 0; mt < 2; ++mt)
; #pragma unroll
;         for (int j = 0; j < 4; ++j) { const int r = wr * 32 + mt * 16 + fq * 4 + j; const float qd = exp2f(lg2 * (float)(r + 1));
; #pragma unroll
;             for (int nt = 0; nt < 4; ++nt) YST[r * 132 + wc * 64 + nt * 16 + fr] = accY[mt][nt][j] * qd; }
;     __syncthreads();
;     { const int i = tid >> 2, part = tid & 3; float yv[32]; float s = 0.f;
	v_mfma_f32_16x16x32_bf16 v[40:43], v[36:39], v[48:51], v[40:43]
	v_mfma_f32_16x16x32_bf16 v[32:35], v[44:47], v[48:51], v[32:35]
	s_waitcnt lgkmcnt(0)
	v_mfma_f32_16x16x32_bf16 v[4:7], v[36:39], v[52:55], v[4:7]
	v_mfma_f32_16x16x32_bf16 v[8:11], v[44:47], v[52:55], v[8:11]
	v_cmp_gt_f32_e32 vcc, s37, v57
	s_and_b64 s[26:27], vcc, exec
	s_cselect_b32 s26, 32, 0
	v_ldexp_f32 v36, v57, s26
	v_lshl_or_b32 v0, v0, 2, v3
	v_log_f32_e32 v36, v36
	v_or_b32_e32 v3, 1, v0
	v_cvt_f32_i32_e32 v3, v3
	v_cndmask_b32_e32 v28, 0, v63, vcc
	v_sub_f32_e32 v28, v36, v28
	v_lshlrev_b32_e32 v1, 2, v1
	v_mul_f32_e32 v36, v28, v3
	v_cmp_gt_f32_e32 vcc, s30, v36
	v_lshlrev_b32_e32 v2, 5, v2
	s_nop 0
	v_cndmask_b32_e32 v36, 0, v62, vcc
	v_fmac_f32_e32 v36, v28, v3
	v_exp_f32_e32 v3, v36
	v_cndmask_b32_e32 v37, 0, v64, vcc
	v_lshl_add_u32 v36, v56, 8, 0
	v_ldexp_f32 v3, v3, v37
	v_mul_lo_u32 v37, v0, s40
	v_add3_u32 v1, v36, v1, v37
	v_or_b32_e32 v36, 2, v0
	v_cvt_f32_i32_e32 v36, v36
	v_mul_f32_e32 v20, v3, v20
	v_mul_f32_e32 v24, v3, v24
	v_add_u32_e32 v37, 0x8800, v1
	ds_write2_b32 v37, v20, v24 offset1:16
	v_mul_f32_e32 v24, v28, v36
	v_cmp_gt_f32_e32 vcc, s30, v24
	v_mul_f32_e32 v20, v3, v40
	v_mul_f32_e32 v3, v3, v4
	v_cndmask_b32_e32 v24, 0, v62, vcc
	v_fmac_f32_e32 v24, v28, v36
	v_exp_f32_e32 v24, v24
	ds_write2_b32 v37, v20, v3 offset0:32 offset1:48
	v_or_b32_e32 v20, 3, v0
	v_cvt_f32_i32_e32 v20, v20
	v_cndmask_b32_e32 v3, 0, v64, vcc
	v_ldexp_f32 v3, v24, v3
	v_mul_f32_e32 v4, v3, v21
	v_mul_f32_e32 v21, v3, v25
	ds_write2_b32 v37, v4, v21 offset0:132 offset1:148
	v_mul_f32_e32 v21, v28, v20
	v_cmp_gt_f32_e32 vcc, s30, v21
	v_mul_f32_e32 v4, v3, v41
	v_mul_f32_e32 v3, v3, v5
	v_cndmask_b32_e32 v21, 0, v62, vcc
	v_fmac_f32_e32 v21, v28, v20
	v_exp_f32_e32 v20, v21
	ds_write2_b32 v37, v4, v3 offset0:164 offset1:180
	v_cndmask_b32_e32 v3, 0, v64, vcc
	v_add_u32_e32 v21, 0x8c00, v1
	v_ldexp_f32 v3, v20, v3
	v_add_u32_e32 v20, 4, v0
	v_cvt_f32_i32_e32 v20, v20
	v_mul_f32_e32 v4, v3, v22
	v_mul_f32_e32 v5, v3, v26
	ds_write2_b32 v21, v4, v5 offset0:8 offset1:24
	v_mul_f32_e32 v5, v28, v20
	v_cmp_gt_f32_e32 vcc, s30, v5
	v_mul_f32_e32 v4, v3, v42
	v_mul_f32_e32 v3, v3, v6
	v_cndmask_b32_e32 v5, 0, v62, vcc
	v_fmac_f32_e32 v5, v28, v20
	v_exp_f32_e32 v5, v5
	ds_write2_b32 v21, v4, v3 offset0:40 offset1:56
	v_cndmask_b32_e32 v3, 0, v64, vcc
	v_ldexp_f32 v3, v5, v3
	v_or_b32_e32 v5, 17, v0
	v_cvt_f32_i32_e32 v5, v5
	v_mul_f32_e32 v4, v3, v23
	v_mul_f32_e32 v6, v3, v27
	ds_write2_b32 v21, v4, v6 offset0:140 offset1:156
	v_mul_f32_e32 v6, v28, v5
	v_cmp_gt_f32_e32 vcc, s30, v6
	v_mul_f32_e32 v4, v3, v43
	v_mul_f32_e32 v3, v3, v7
	v_cndmask_b32_e32 v6, 0, v62, vcc
	v_fmac_f32_e32 v6, v28, v5
	v_exp_f32_e32 v5, v6
	v_or_b32_e32 v6, 18, v0
	v_cvt_f32_i32_e32 v6, v6
	ds_write2_b32 v21, v4, v3 offset0:172 offset1:188
	v_cndmask_b32_e32 v3, 0, v64, vcc
	v_ldexp_f32 v3, v5, v3
	v_mul_f32_e32 v4, v3, v12
	v_mul_f32_e32 v5, v3, v16
	v_add_u32_e32 v7, 0xa800, v1
	ds_write2_b32 v7, v4, v5 offset0:64 offset1:80
	v_mul_f32_e32 v5, v28, v6
	v_cmp_gt_f32_e32 vcc, s30, v5
	v_mul_f32_e32 v4, v3, v32
	v_mul_f32_e32 v3, v3, v8
	v_cndmask_b32_e32 v5, 0, v62, vcc
	v_fmac_f32_e32 v5, v28, v6
	v_exp_f32_e32 v5, v5
	ds_write2_b32 v7, v4, v3 offset0:96 offset1:112
	v_cndmask_b32_e32 v3, 0, v64, vcc
	v_add_u32_e32 v1, 0xac00, v1
	v_ldexp_f32 v3, v5, v3
	v_or_b32_e32 v5, 19, v0
	v_cvt_f32_i32_e32 v5, v5
	v_mul_f32_e32 v4, v3, v13
	v_mul_f32_e32 v6, v3, v17
	ds_write2_b32 v7, v4, v6 offset0:196 offset1:212
	v_mul_f32_e32 v6, v28, v5
	v_cmp_gt_f32_e32 vcc, s30, v6
	v_add_u32_e32 v0, 20, v0
	v_mul_f32_e32 v4, v3, v33
	v_cndmask_b32_e32 v6, 0, v62, vcc
	v_fmac_f32_e32 v6, v28, v5
	v_exp_f32_e32 v5, v6
	v_mul_f32_e32 v3, v3, v9
	v_cvt_f32_i32_e32 v0, v0
	ds_write2_b32 v7, v4, v3 offset0:228 offset1:244
	v_cndmask_b32_e32 v3, 0, v64, vcc
	v_ldexp_f32 v3, v5, v3
	v_mul_f32_e32 v4, v3, v14
	v_mul_f32_e32 v5, v3, v18
	ds_write2_b32 v1, v4, v5 offset0:72 offset1:88
	v_mul_f32_e32 v5, v28, v0
	v_cmp_gt_f32_e32 vcc, s30, v5
	v_mul_f32_e32 v4, v3, v34
	v_mul_f32_e32 v3, v3, v10
	v_cndmask_b32_e32 v5, 0, v62, vcc
	v_fmac_f32_e32 v5, v28, v0
	v_exp_f32_e32 v0, v5
	ds_write2_b32 v1, v4, v3 offset0:104 offset1:120
	v_cndmask_b32_e32 v3, 0, v64, vcc
	v_and_b32_e32 v10, 0x60, v2
	v_ldexp_f32 v0, v0, v3
	v_mul_f32_e32 v3, v0, v15
	v_mul_f32_e32 v4, v0, v19
	ds_write2_b32 v1, v3, v4 offset0:204 offset1:220
	v_add_u32_e32 v4, s45, v66
	v_mul_f32_e32 v3, v0, v35
	v_mul_f32_e32 v0, v0, v11
	v_ashrrev_i32_e32 v5, 31, v4
	ds_write2_b32 v1, v3, v0 offset0:236 offset1:252
	v_lshlrev_b64 v[0:1], 11, v[4:5]
	v_lshl_add_u64 v[6:7], s[10:11], 0, v[0:1]
	v_lshl_add_u64 v[0:1], v[6:7], 0, s[18:19]
	v_lshlrev_b32_e32 v28, 1, v10
	v_lshl_add_u64 v[8:9], v[0:1], 0, v[28:29]
	v_mad_i64_i32 v[4:5], s[26:27], v4, s42, v[6:7]
	v_add_co_u32_e32 v34, vcc, s41, v8
	v_lshl_add_u64 v[4:5], v[4:5], 0, s[18:19]
	s_nop 0
	v_addc_co_u32_e32 v35, vcc, 0, v9, vcc
	v_lshl_add_u64 v[12:13], v[4:5], 0, v[28:29]
	v_lshl_add_u64 v[32:33], v[8:9], 0, s[22:23]
	v_add_co_u32_e32 v4, vcc, s43, v12
	s_waitcnt lgkmcnt(0)
	s_barrier
; #define LAS __attribute__((address_space(3)))
; __device__ __forceinline__ float lo_bf(unsigned x) { return __uint_as_float(x << 16); }
; __device__ __forceinline__ float hi_bf(unsigned x) { return __uint_as_float(x & 0xffff0000u); }
; __device__ __forceinline__ float quad_sum(float v) { v += dppf<0xB1>(v); v += dppf<0x4E>(v); return v; }
; __device__ __forceinline__ void ret_unit_c(PR P, LAS unsigned char* lds, const int bh, const int n, const int wv) {
;     ...
;     { const int i = tid >> 2, part = tid & 3; float yv[32]; float s = 0.f;
;       bf16_t* yo = Y + (size_t)(row0 + i) * 1024 + 512 + h * 128 + part * 32;
; #pragma unroll
;       for (int x = 0; x < 4; ++x) { const u32x4 y1 = *(const u32x4*)(yo + x * 8); const f32x4 ta = *(const LAS f32x4*)(YST + i * 132 + part * 32 + x * 8), tb = *(const LAS f32x4*)(YST + i * 132 + part * 32 + x * 8 + 4);
;           yv[x * 8 + 0] = ta[0] + lo_bf(y1.x); yv[x * 8 + 1] = ta[1] + hi_bf(y1.x); yv[x * 8 + 2] = ta[2] + lo_bf(y1.y); yv[x * 8 + 3] = ta[3] + hi_bf(y1.y);
;           yv[x * 8 + 4] = tb[0] + lo_bf(y1.z); yv[x * 8 + 5] = tb[1] + hi_bf(y1.z); yv[x * 8 + 6] = tb[2] + lo_bf(y1.w); yv[x * 8 + 7] = tb[3] + hi_bf(y1.w); }
; #pragma unroll
;       for (int x = 0; x < 32; ++x) s += yv[x];
;       s = quad_sum(s); const float mean = s * (1.0f / 128.0f); float s2 = 0.f;
; #pragma unroll
;       for (int x = 0; x < 32; ++x) { yv[x] -= mean; s2 += yv[x] * yv[x]; }
;       s2 = quad_sum(s2); const float rstd = rsqrtf(s2 * (1.0f / 128.0f) + 1e-5f);
;       const bf16_t* gp = PS + (size_t)(row0 + i) * NCOLS + 1792 + 1536 + h * 128 + part * 32; const float* gw = P.gn_w + h * 128 + part * 32;
; #pragma unroll
;       for (int x = 0; x < 4; ++x) { const u32x4 g4 = *(const u32x4*)(gp + x * 8); const float4 w0 = *(const float4*)(gw + x * 8), w1 = *(const float4*)(gw + x * 8 + 4);
;           const float gg[8] = {lo_bf(g4.x), hi_bf(g4.x), lo_bf(g4.y), hi_bf(g4.y), lo_bf(g4.z), hi_bf(g4.z), lo_bf(g4.w), hi_bf(g4.w)}; const float ww[8] = {w0.x, w0.y, w0.z, w0.w, w1.x, w1.y, w1.z, w1.w};
;           float o[8];
; #pragma unroll
;           for (int z = 0; z < 8; ++z) o[z] = yv[x * 8 + z] * rstd * ww[z] * (gg[z] * __builtin_amdgcn_rcpf(1.0f + __expf(-gg[z])));
	global_load_dwordx4 v[0:3], v[32:33], off offset:48
	v_addc_co_u32_e32 v5, vcc, 0, v13, vcc
	global_load_dwordx4 v[58:61], v[4:5], off offset:512
	global_load_dwordx4 v[52:55], v[34:35], off offset:3072
	v_mul_lo_u32 v4, v66, s40
	global_load_dwordx4 v[20:23], v[32:33], off offset:32
	global_load_dwordx4 v[66:69], v[32:33], off offset:16
	v_lshlrev_b32_e32 v28, 2, v10
	v_add3_u32 v8, 0, v4, v28
	ds_read_b128 v[70:73], v8 offset:34816
	ds_read_b128 v[44:47], v8 offset:34832
	ds_read_b128 v[74:77], v8 offset:34848
	ds_read_b128 v[78:81], v8 offset:34864
	ds_read_b128 v[4:7], v8 offset:34912
	ds_read_b128 v[24:27], v8 offset:34880
	ds_read_b128 v[82:85], v8 offset:34896
	ds_read_b128 v[8:11], v8 offset:34928
	s_lshl_b32 s18, s44, 9
	s_add_u32 s26, s12, s18
	s_addc_u32 s27, s13, 0
	s_addk_i32 s28, 0x80
	s_cmpk_eq_i32 s28, 0x180
	s_waitcnt vmcnt(4)
	v_and_b32_e32 v15, 0xffff0000, v0
	v_lshlrev_b32_e32 v14, 16, v0
	s_waitcnt lgkmcnt(3)
	v_pk_add_f32 v[40:41], v[4:5], v[14:15]
	v_and_b32_e32 v5, 0xffff0000, v1
	v_lshlrev_b32_e32 v4, 16, v1
	v_and_b32_e32 v1, 0xffff0000, v2
	v_lshlrev_b32_e32 v0, 16, v2
	s_waitcnt vmcnt(3)
	v_lshlrev_b32_e32 v38, 16, v60
	s_waitcnt lgkmcnt(0)
	v_pk_add_f32 v[48:49], v[8:9], v[0:1]
	v_lshl_add_u64 v[8:9], v[12:13], 0, s[24:25]
	s_waitcnt vmcnt(2)
	v_lshlrev_b32_e32 v12, 16, v55
	v_and_b32_e32 v13, 0xffff0000, v55
	v_and_b32_e32 v39, 0xffff0000, v60
	v_mul_f32_e32 v37, 0xbfb8aa3b, v38
	v_pk_add_f32 v[56:57], v[46:47], v[12:13]
	v_exp_f32_e32 v46, v37
	v_mul_f32_e32 v37, 0xbfb8aa3b, v39
	v_exp_f32_e32 v47, v37
	v_lshlrev_b32_e32 v36, 16, v61
	v_add_f32_e32 v46, 1.0, v46
	v_rcp_f32_e32 v46, v46
	v_add_f32_e32 v47, 1.0, v47
	v_rcp_f32_e32 v47, v47
	v_and_b32_e32 v37, 0xffff0000, v61
	v_lshlrev_b32_e32 v60, 16, v54
	v_and_b32_e32 v61, 0xffff0000, v54
	v_pk_add_f32 v[60:61], v[44:45], v[60:61]
	v_lshlrev_b32_e32 v44, 16, v59
	v_and_b32_e32 v45, 0xffff0000, v59
	v_pk_mul_f32 v[38:39], v[46:47], v[38:39]
	v_lshlrev_b32_e32 v46, 16, v53
	v_and_b32_e32 v47, 0xffff0000, v53
	v_mul_f32_e32 v53, 0xbfb8aa3b, v44
	v_mul_f32_e32 v54, 0xbfb8aa3b, v45
	v_exp_f32_e32 v53, v53
	v_exp_f32_e32 v54, v54
	v_pk_add_f32 v[72:73], v[72:73], v[46:47]
	v_and_b32_e32 v55, 0xffff0000, v52
	v_add_f32_e32 v46, 1.0, v53
	v_add_f32_e32 v47, 1.0, v54
	v_lshlrev_b32_e32 v54, 16, v52
	v_lshlrev_b32_e32 v52, 16, v58
	v_and_b32_e32 v53, 0xffff0000, v58
	v_pk_add_f32 v[70:71], v[70:71], v[54:55]
	v_mul_f32_e32 v55, 0xbfb8aa3b, v52
	v_mul_f32_e32 v58, 0xbfb8aa3b, v53
	v_exp_f32_e32 v55, v55
	v_exp_f32_e32 v58, v58
	v_add_f32_e32 v54, 0, v70
	v_add_f32_e32 v59, v71, v54
	v_add_f32_e32 v54, 1.0, v55
	v_add_f32_e32 v55, 1.0, v58
	v_add_f32_e32 v58, v72, v59
	v_mul_f32_e32 v59, 0xbfb8aa3b, v36
	v_mul_f32_e32 v86, 0xbfb8aa3b, v37
	v_add_f32_e32 v58, v73, v58
	v_exp_f32_e32 v59, v59
	v_exp_f32_e32 v86, v86
	v_add_f32_e32 v58, v60, v58
	v_and_b32_e32 v1, 0xffff0000, v3
	v_lshlrev_b32_e32 v0, 16, v3
	v_add_f32_e32 v58, v61, v58
	v_pk_add_f32 v[42:43], v[6:7], v[4:5]
	v_pk_add_f32 v[50:51], v[10:11], v[0:1]
	global_load_dwordx4 v[0:3], v[8:9], off offset:48
	global_load_dwordx4 v[4:7], v[8:9], off offset:32
	s_nop 0
	global_load_dwordx4 v[8:11], v[8:9], off offset:16
	s_nop 0
	global_load_dwordx4 v[12:15], v28, s[26:27] offset:16
	global_load_dwordx4 v[16:19], v28, s[26:27]
	v_add_f32_e32 v58, v56, v58
	v_add_f32_e32 v88, v57, v58
	v_add_f32_e32 v58, 1.0, v59
	v_add_f32_e32 v59, 1.0, v86
	s_waitcnt vmcnt(5)
	v_lshlrev_b32_e32 v86, 16, v69
	v_and_b32_e32 v87, 0xffff0000, v69
	v_pk_add_f32 v[80:81], v[80:81], v[86:87]
	v_lshlrev_b32_e32 v86, 16, v68
	v_and_b32_e32 v87, 0xffff0000, v68
	v_pk_add_f32 v[68:69], v[78:79], v[86:87]
	v_lshlrev_b32_e32 v78, 16, v67
	v_and_b32_e32 v79, 0xffff0000, v67
	v_pk_add_f32 v[76:77], v[76:77], v[78:79]
	v_lshlrev_b32_e32 v78, 16, v66
	v_and_b32_e32 v79, 0xffff0000, v66
	v_pk_add_f32 v[66:67], v[74:75], v[78:79]
	v_lshlrev_b32_e32 v78, 16, v22
	v_add_f32_e32 v74, v66, v88
	v_add_f32_e32 v74, v67, v74
	v_add_f32_e32 v74, v76, v74
	v_add_f32_e32 v74, v77, v74
	v_add_f32_e32 v74, v68, v74
	v_add_f32_e32 v74, v69, v74
	v_add_f32_e32 v74, v80, v74
	v_and_b32_e32 v79, 0xffff0000, v22
	v_add_f32_e32 v86, v81, v74
	v_lshlrev_b32_e32 v74, 16, v23
	v_and_b32_e32 v75, 0xffff0000, v23
	v_pk_add_f32 v[22:23], v[82:83], v[78:79]
	v_lshlrev_b32_e32 v78, 16, v21
	v_and_b32_e32 v79, 0xffff0000, v21
	v_pk_add_f32 v[26:27], v[26:27], v[78:79]
	v_lshlrev_b32_e32 v78, 16, v20
	v_and_b32_e32 v79, 0xffff0000, v20
	v_pk_add_f32 v[20:21], v[24:25], v[78:79]
	v_pk_add_f32 v[74:75], v[84:85], v[74:75]
	v_add_f32_e32 v24, v20, v86
	v_add_f32_e32 v24, v21, v24
	v_add_f32_e32 v24, v26, v24
	v_add_f32_e32 v24, v27, v24
	v_add_f32_e32 v24, v22, v24
	v_add_f32_e32 v24, v23, v24
	v_add_f32_e32 v24, v74, v24
	v_add_f32_e32 v24, v75, v24
	v_add_f32_e32 v24, v40, v24
	v_add_f32_e32 v24, v41, v24
	v_add_f32_e32 v24, v42, v24
	v_add_f32_e32 v24, v43, v24
	v_add_f32_e32 v24, v48, v24
	v_add_f32_e32 v24, v49, v24
	v_add_f32_e32 v24, v50, v24
	v_add_f32_e32 v24, v51, v24
	v_rcp_f32_e32 v46, v46
	v_rcp_f32_e32 v47, v47
	v_add_f32_dpp v24, v24, v24 quad_perm:[1,0,3,2] row_mask:0xf bank_mask:0xf bound_ctrl:1
	v_rcp_f32_e32 v54, v54
	v_rcp_f32_e32 v55, v55
	v_add_f32_dpp v24, v24, v24 quad_perm:[2,3,0,1] row_mask:0xf bank_mask:0xf bound_ctrl:1
	v_mul_f32_e32 v78, 0x3c000000, v24
	v_pk_add_f32 v[70:71], v[70:71], v[78:79] op_sel_hi:[1,0] neg_lo:[0,1] neg_hi:[0,1]
	v_pk_add_f32 v[72:73], v[72:73], v[78:79] op_sel_hi:[1,0] neg_lo:[0,1] neg_hi:[0,1]
	v_pk_mul_f32 v[82:83], v[70:71], v[70:71]
	v_pk_mul_f32 v[84:85], v[72:73], v[72:73]
	v_add_f32_e32 v82, v82, v83
; __device__ __forceinline__ unsigned cvt_pk_bf16(float lo, float hi) { const f32x2_t v = {lo, hi}; const bf16x2_t b = __builtin_convertvector(v, bf16x2_t); return __builtin_bit_cast(unsigned, b); }
; __device__ __forceinline__ float lo_bf(unsigned x) { return __uint_as_float(x << 16); }
; __device__ __forceinline__ float hi_bf(unsigned x) { return __uint_as_float(x & 0xffff0000u); }
; __device__ __forceinline__ float quad_sum(float v) { v += dppf<0xB1>(v); v += dppf<0x4E>(v); return v; }
; __device__ __forceinline__ void ret_unit_c(PR P, LAS unsigned char* lds, const int bh, const int n, const int wv) {
;     ...
;       s = quad_sum(s); const float mean = s * (1.0f / 128.0f); float s2 = 0.f;
; #pragma unroll
;       for (int x = 0; x < 32; ++x) { yv[x] -= mean; s2 += yv[x] * yv[x]; }
;       s2 = quad_sum(s2); const float rstd = rsqrtf(s2 * (1.0f / 128.0f) + 1e-5f);
;       const bf16_t* gp = PS + (size_t)(row0 + i) * NCOLS + 1792 + 1536 + h * 128 + part * 32; const float* gw = P.gn_w + h * 128 + part * 32;
; #pragma unroll
;       for (int x = 0; x < 4; ++x) { const u32x4 g4 = *(const u32x4*)(gp + x * 8); const float4 w0 = *(const float4*)(gw + x * 8), w1 = *(const float4*)(gw + x * 8 + 4);
;           const float gg[8] = {lo_bf(g4.x), hi_bf(g4.x), lo_bf(g4.y), hi_bf(g4.y), lo_bf(g4.z), hi_bf(g4.z), lo_bf(g4.w), hi_bf(g4.w)}; const float ww[8] = {w0.x, w0.y, w0.z, w0.w, w1.x, w1.y, w1.z, w1.w};
;           float o[8];
; #pragma unroll
;           for (int z = 0; z < 8; ++z) o[z] = yv[x * 8 + z] * rstd * ww[z] * (gg[z] * __builtin_amdgcn_rcpf(1.0f + __expf(-gg[z])));
;           u32x4 w; w.x = pg8::cvt_pk_bf16(o[0], o[1]); w.y = pg8::cvt_pk_bf16(o[2], o[3]); w.z = pg8::cvt_pk_bf16(o[4], o[5]); w.w = pg8::cvt_pk_bf16(o[6], o[7]);
;           *(u32x4*)(yo + x * 8) = w; } }
	v_pk_add_f32 v[60:61], v[60:61], v[78:79] op_sel_hi:[1,0] neg_lo:[0,1] neg_hi:[0,1]
	v_add_f32_e32 v82, v84, v82
	v_pk_mul_f32 v[86:87], v[60:61], v[60:61]
	v_add_f32_e32 v82, v85, v82
	v_pk_add_f32 v[56:57], v[56:57], v[78:79] op_sel_hi:[1,0] neg_lo:[0,1] neg_hi:[0,1]
	v_add_f32_e32 v82, v86, v82
	v_pk_mul_f32 v[88:89], v[56:57], v[56:57]
	v_add_f32_e32 v82, v87, v82
	v_pk_add_f32 v[66:67], v[66:67], v[78:79] op_sel_hi:[1,0] neg_lo:[0,1] neg_hi:[0,1]
	v_add_f32_e32 v82, v88, v82
	v_pk_mul_f32 v[90:91], v[66:67], v[66:67]
	v_add_f32_e32 v82, v89, v82
	v_pk_add_f32 v[76:77], v[76:77], v[78:79] op_sel_hi:[1,0] neg_lo:[0,1] neg_hi:[0,1]
	v_add_f32_e32 v82, v90, v82
	v_pk_mul_f32 v[92:93], v[76:77], v[76:77]
	v_add_f32_e32 v82, v91, v82
	v_pk_add_f32 v[68:69], v[68:69], v[78:79] op_sel_hi:[1,0] neg_lo:[0,1] neg_hi:[0,1]
	v_add_f32_e32 v82, v92, v82
	v_pk_mul_f32 v[94:95], v[68:69], v[68:69]
	v_add_f32_e32 v82, v93, v82
	v_pk_add_f32 v[80:81], v[80:81], v[78:79] op_sel_hi:[1,0] neg_lo:[0,1] neg_hi:[0,1]
	v_add_f32_e32 v82, v94, v82
	v_pk_mul_f32 v[96:97], v[80:81], v[80:81]
	v_add_f32_e32 v82, v95, v82
	v_pk_add_f32 v[98:99], v[20:21], v[78:79] op_sel_hi:[1,0] neg_lo:[0,1] neg_hi:[0,1]
	v_add_f32_e32 v82, v96, v82
	v_pk_mul_f32 v[100:101], v[98:99], v[98:99]
	v_add_f32_e32 v82, v97, v82
	v_pk_add_f32 v[26:27], v[26:27], v[78:79] op_sel_hi:[1,0] neg_lo:[0,1] neg_hi:[0,1]
	v_add_f32_e32 v82, v100, v82
	v_pk_mul_f32 v[102:103], v[26:27], v[26:27]
	v_add_f32_e32 v82, v101, v82
	v_pk_add_f32 v[104:105], v[22:23], v[78:79] op_sel_hi:[1,0] neg_lo:[0,1] neg_hi:[0,1]
	v_add_f32_e32 v82, v102, v82
	v_pk_mul_f32 v[106:107], v[104:105], v[104:105]
	v_add_f32_e32 v82, v103, v82
	v_pk_add_f32 v[74:75], v[74:75], v[78:79] op_sel_hi:[1,0] neg_lo:[0,1] neg_hi:[0,1]
	v_add_f32_e32 v82, v106, v82
	v_pk_mul_f32 v[108:109], v[74:75], v[74:75]
	v_add_f32_e32 v82, v107, v82
	v_pk_add_f32 v[40:41], v[40:41], v[78:79] op_sel_hi:[1,0] neg_lo:[0,1] neg_hi:[0,1]
	v_add_f32_e32 v82, v108, v82
	v_pk_add_f32 v[22:23], v[48:49], v[78:79] op_sel_hi:[1,0] neg_lo:[0,1] neg_hi:[0,1]
	v_pk_add_f32 v[20:21], v[50:51], v[78:79] op_sel_hi:[1,0] neg_lo:[0,1] neg_hi:[0,1]
	v_pk_add_f32 v[24:25], v[42:43], v[78:79] op_sel_hi:[1,0] neg_lo:[0,1] neg_hi:[0,1]
	v_pk_mul_f32 v[78:79], v[40:41], v[40:41]
	v_add_f32_e32 v82, v109, v82
	v_add_f32_e32 v78, v78, v82
	v_pk_mul_f32 v[42:43], v[24:25], v[24:25]
	v_add_f32_e32 v78, v79, v78
	v_add_f32_e32 v42, v42, v78
	v_pk_mul_f32 v[48:49], v[22:23], v[22:23]
	v_add_f32_e32 v42, v43, v42
	v_add_f32_e32 v42, v48, v42
	v_pk_mul_f32 v[50:51], v[20:21], v[20:21]
	v_add_f32_e32 v42, v49, v42
	v_add_f32_e32 v42, v50, v42
	v_add_f32_e32 v42, v51, v42
	v_rcp_f32_e32 v58, v58
	v_rcp_f32_e32 v59, v59
	v_add_f32_dpp v42, v42, v42 quad_perm:[1,0,3,2] row_mask:0xf bank_mask:0xf bound_ctrl:1
	v_pk_mul_f32 v[36:37], v[58:59], v[36:37]
	s_nop 0
	v_add_f32_dpp v42, v42, v42 quad_perm:[2,3,0,1] row_mask:0xf bank_mask:0xf bound_ctrl:1
	v_fmamk_f32 v42, v42, 0x3c000000, v65
	v_mul_f32_e32 v43, 0x4b800000, v42
	v_cmp_gt_f32_e32 vcc, s37, v42
	s_nop 1
	v_cndmask_b32_e32 v42, v42, v43, vcc
	v_rsq_f32_e32 v48, v42
	v_pk_mul_f32 v[42:43], v[46:47], v[44:45]
	v_pk_mul_f32 v[44:45], v[54:55], v[52:53]
	v_mul_f32_e32 v46, 0x45800000, v48
	v_cndmask_b32_e32 v46, v48, v46, vcc
	v_pk_mul_f32 v[48:49], v[70:71], v[46:47] op_sel_hi:[1,0]
	s_waitcnt vmcnt(0)
	v_pk_mul_f32 v[16:17], v[16:17], v[48:49]
	s_nop 0
	v_pk_mul_f32 v[16:17], v[44:45], v[16:17]
	v_pk_mul_f32 v[44:45], v[72:73], v[46:47] op_sel_hi:[1,0]
	s_nop 0
	v_pk_mul_f32 v[18:19], v[18:19], v[44:45]
	v_and_b32_e32 v45, 0xffff0000, v8
	v_pk_mul_f32 v[18:19], v[42:43], v[18:19]
	v_pk_mul_f32 v[42:43], v[60:61], v[46:47] op_sel_hi:[1,0]
	v_lshlrev_b32_e32 v44, 16, v8
	v_pk_mul_f32 v[12:13], v[12:13], v[42:43]
	v_mul_f32_e32 v8, 0xbfb8aa3b, v44
	v_pk_mul_f32 v[38:39], v[38:39], v[12:13]
	v_pk_mul_f32 v[12:13], v[56:57], v[46:47] op_sel_hi:[1,0]
	v_exp_f32_e32 v8, v8
	v_pk_mul_f32 v[12:13], v[14:15], v[12:13]
	v_cvt_pk_bf16_f32 v14, v38, v39
	v_pk_mul_f32 v[36:37], v[36:37], v[12:13]
	v_cvt_pk_bf16_f32 v12, v16, v17
	v_cvt_pk_bf16_f32 v13, v18, v19
	v_cvt_pk_bf16_f32 v15, v36, v37
	global_store_dwordx4 v[34:35], v[12:15], off offset:3072
	global_load_dwordx4 v[12:15], v28, s[26:27] offset:32
	s_nop 0
	global_load_dwordx4 v[16:19], v28, s[26:27] offset:48
	v_and_b32_e32 v37, 0xffff0000, v10
	v_mul_f32_e32 v35, 0xbfb8aa3b, v37
	v_exp_f32_e32 v38, v35
	v_lshlrev_b32_e32 v34, 16, v11
	v_and_b32_e32 v35, 0xffff0000, v11
	v_and_b32_e32 v39, 0xffff0000, v9
	v_add_f32_e32 v11, 1.0, v38
	v_lshlrev_b32_e32 v38, 16, v9
	v_mul_f32_e32 v9, 0xbfb8aa3b, v38
	v_exp_f32_e32 v9, v9
	v_mul_f32_e32 v42, 0xbfb8aa3b, v39
	v_exp_f32_e32 v43, v42
	v_lshlrev_b32_e32 v36, 16, v10
	v_add_f32_e32 v9, 1.0, v9
	v_rcp_f32_e32 v42, v9
	v_add_f32_e32 v9, 1.0, v43
	v_mul_f32_e32 v43, 0xbfb8aa3b, v45
	v_exp_f32_e32 v47, v43
	v_mul_f32_e32 v10, 0xbfb8aa3b, v36
	v_exp_f32_e32 v10, v10
	v_rcp_f32_e32 v43, v9
	v_add_f32_e32 v9, 1.0, v47
	v_mul_f32_e32 v47, 0xbfb8aa3b, v34
	v_exp_f32_e32 v47, v47
	v_mul_f32_e32 v48, 0xbfb8aa3b, v35
	v_add_f32_e32 v10, 1.0, v10
	v_exp_f32_e32 v49, v48
	v_rcp_f32_e32 v10, v10
	v_rcp_f32_e32 v11, v11
	v_add_f32_e32 v8, 1.0, v8
	v_rcp_f32_e32 v8, v8
	v_rcp_f32_e32 v9, v9
	v_add_f32_e32 v47, 1.0, v47
	v_rcp_f32_e32 v48, v47
	v_add_f32_e32 v47, 1.0, v49
	v_pk_mul_f32 v[10:11], v[10:11], v[36:37]
	v_pk_mul_f32 v[36:37], v[42:43], v[38:39]
	v_pk_mul_f32 v[38:39], v[66:67], v[46:47] op_sel_hi:[1,0]
	v_pk_mul_f32 v[8:9], v[8:9], v[44:45]
	v_rcp_f32_e32 v49, v47
	s_waitcnt vmcnt(1)
; __device__ __forceinline__ unsigned cvt_pk_bf16(float lo, float hi) { const f32x2_t v = {lo, hi}; const bf16x2_t b = __builtin_convertvector(v, bf16x2_t); return __builtin_bit_cast(unsigned, b); }
; __device__ __forceinline__ float lo_bf(unsigned x) { return __uint_as_float(x << 16); }
; __device__ __forceinline__ float hi_bf(unsigned x) { return __uint_as_float(x & 0xffff0000u); }
; __device__ __forceinline__ void ret_unit_c(PR P, LAS unsigned char* lds, const int bh, const int n, const int wv) {
;     ...
; #pragma unroll
;       for (int x = 0; x < 4; ++x) { const u32x4 g4 = *(const u32x4*)(gp + x * 8); const float4 w0 = *(const float4*)(gw + x * 8), w1 = *(const float4*)(gw + x * 8 + 4);
;           const float gg[8] = {lo_bf(g4.x), hi_bf(g4.x), lo_bf(g4.y), hi_bf(g4.y), lo_bf(g4.z), hi_bf(g4.z), lo_bf(g4.w), hi_bf(g4.w)}; const float ww[8] = {w0.x, w0.y, w0.z, w0.w, w1.x, w1.y, w1.z, w1.w};
;           float o[8];
; #pragma unroll
;           for (int z = 0; z < 8; ++z) o[z] = yv[x * 8 + z] * rstd * ww[z] * (gg[z] * __builtin_amdgcn_rcpf(1.0f + __expf(-gg[z])));
;           u32x4 w; w.x = pg8::cvt_pk_bf16(o[0], o[1]); w.y = pg8::cvt_pk_bf16(o[2], o[3]); w.z = pg8::cvt_pk_bf16(o[4], o[5]); w.w = pg8::cvt_pk_bf16(o[6], o[7]);
;           *(u32x4*)(yo + x * 8) = w; } }
;     __syncthreads();
	v_pk_mul_f32 v[12:13], v[12:13], v[38:39]
	s_nop 0
	v_pk_mul_f32 v[8:9], v[8:9], v[12:13]
	v_pk_mul_f32 v[12:13], v[76:77], v[46:47] op_sel_hi:[1,0]
	v_pk_mul_f32 v[34:35], v[48:49], v[34:35]
	v_pk_mul_f32 v[12:13], v[14:15], v[12:13]
	v_pk_mul_f32 v[14:15], v[68:69], v[46:47] op_sel_hi:[1,0]
	v_pk_mul_f32 v[12:13], v[36:37], v[12:13]
	s_waitcnt vmcnt(0)
	v_pk_mul_f32 v[14:15], v[16:17], v[14:15]
	v_cvt_pk_bf16_f32 v8, v8, v9
	v_pk_mul_f32 v[10:11], v[10:11], v[14:15]
	v_pk_mul_f32 v[14:15], v[80:81], v[46:47] op_sel_hi:[1,0]
	v_cvt_pk_bf16_f32 v9, v12, v13
	v_pk_mul_f32 v[14:15], v[18:19], v[14:15]
	v_cvt_pk_bf16_f32 v10, v10, v11
	v_pk_mul_f32 v[14:15], v[34:35], v[14:15]
	v_and_b32_e32 v19, 0xffff0000, v6
	v_cvt_pk_bf16_f32 v11, v14, v15
	global_store_dwordx4 v[32:33], v[8:11], off offset:16
	global_load_dwordx4 v[8:11], v28, s[26:27] offset:64
	s_nop 0
	global_load_dwordx4 v[12:15], v28, s[26:27] offset:80
	v_mul_f32_e32 v17, 0xbfb8aa3b, v19
	v_exp_f32_e32 v34, v17
	v_lshlrev_b32_e32 v16, 16, v7
	v_and_b32_e32 v17, 0xffff0000, v7
	v_and_b32_e32 v35, 0xffff0000, v5
	v_add_f32_e32 v7, 1.0, v34
	v_lshlrev_b32_e32 v34, 16, v5
	v_mul_f32_e32 v5, 0xbfb8aa3b, v34
	v_exp_f32_e32 v5, v5
	v_mul_f32_e32 v36, 0xbfb8aa3b, v35
	v_exp_f32_e32 v37, v36
	v_lshlrev_b32_e32 v18, 16, v6
	v_mul_f32_e32 v6, 0xbfb8aa3b, v18
	v_add_f32_e32 v5, 1.0, v5
	v_lshlrev_b32_e32 v38, 16, v4
	v_and_b32_e32 v39, 0xffff0000, v4
	v_exp_f32_e32 v6, v6
	v_rcp_f32_e32 v36, v5
	v_add_f32_e32 v5, 1.0, v37
	v_mul_f32_e32 v4, 0xbfb8aa3b, v38
	v_mul_f32_e32 v37, 0xbfb8aa3b, v39
	v_exp_f32_e32 v4, v4
	v_exp_f32_e32 v42, v37
	v_add_f32_e32 v6, 1.0, v6
	v_rcp_f32_e32 v6, v6
	v_rcp_f32_e32 v7, v7
	v_rcp_f32_e32 v37, v5
	v_add_f32_e32 v4, 1.0, v4
	v_add_f32_e32 v5, 1.0, v42
	v_mul_f32_e32 v42, 0xbfb8aa3b, v16
	v_mul_f32_e32 v43, 0xbfb8aa3b, v17
	v_rcp_f32_e32 v4, v4
	v_exp_f32_e32 v42, v42
	v_exp_f32_e32 v43, v43
	v_rcp_f32_e32 v5, v5
	v_pk_mul_f32 v[6:7], v[6:7], v[18:19]
	v_pk_mul_f32 v[18:19], v[36:37], v[34:35]
	v_pk_mul_f32 v[34:35], v[98:99], v[46:47] op_sel_hi:[1,0]
	v_add_f32_e32 v42, 1.0, v42
	v_add_f32_e32 v43, 1.0, v43
	v_pk_mul_f32 v[4:5], v[4:5], v[38:39]
	v_rcp_f32_e32 v42, v42
	v_rcp_f32_e32 v43, v43
	s_waitcnt vmcnt(1)
	v_pk_mul_f32 v[8:9], v[8:9], v[34:35]
	s_nop 0
	v_pk_mul_f32 v[4:5], v[4:5], v[8:9]
	v_pk_mul_f32 v[8:9], v[26:27], v[46:47] op_sel_hi:[1,0]
	v_pk_mul_f32 v[16:17], v[42:43], v[16:17]
	v_pk_mul_f32 v[8:9], v[10:11], v[8:9]
	v_pk_mul_f32 v[10:11], v[104:105], v[46:47] op_sel_hi:[1,0]
	v_pk_mul_f32 v[8:9], v[18:19], v[8:9]
	s_waitcnt vmcnt(0)
	v_pk_mul_f32 v[10:11], v[12:13], v[10:11]
	v_cvt_pk_bf16_f32 v4, v4, v5
	v_pk_mul_f32 v[6:7], v[6:7], v[10:11]
	v_pk_mul_f32 v[10:11], v[74:75], v[46:47] op_sel_hi:[1,0]
	v_cvt_pk_bf16_f32 v5, v8, v9
	v_pk_mul_f32 v[10:11], v[14:15], v[10:11]
	v_cvt_pk_bf16_f32 v6, v6, v7
	v_pk_mul_f32 v[10:11], v[16:17], v[10:11]
	v_lshlrev_b32_e32 v12, 16, v0
	v_cvt_pk_bf16_f32 v7, v10, v11
	global_store_dwordx4 v[32:33], v[4:7], off offset:32
	global_load_dwordx4 v[4:7], v28, s[26:27] offset:96
	s_nop 0
	global_load_dwordx4 v[8:11], v28, s[26:27] offset:112
	v_and_b32_e32 v13, 0xffff0000, v0
	v_mul_f32_e32 v0, 0xbfb8aa3b, v12
	v_exp_f32_e32 v0, v0
	v_mul_f32_e32 v14, 0xbfb8aa3b, v13
	v_exp_f32_e32 v15, v14
	v_add_f32_e32 v0, 1.0, v0
	v_rcp_f32_e32 v14, v0
	v_add_f32_e32 v0, 1.0, v15
	v_rcp_f32_e32 v15, v0
	v_lshlrev_b32_e32 v0, 16, v1
	v_and_b32_e32 v1, 0xffff0000, v1
	v_pk_mul_f32 v[12:13], v[14:15], v[12:13]
	v_mul_f32_e32 v14, 0xbfb8aa3b, v0
	v_exp_f32_e32 v16, v14
	v_pk_mul_f32 v[14:15], v[40:41], v[46:47] op_sel_hi:[1,0]
	s_waitcnt vmcnt(1)
	v_pk_mul_f32 v[4:5], v[4:5], v[14:15]
	s_nop 0
	v_pk_mul_f32 v[4:5], v[12:13], v[4:5]
	v_mul_f32_e32 v13, 0xbfb8aa3b, v1
	v_exp_f32_e32 v13, v13
	v_add_f32_e32 v12, 1.0, v16
	v_rcp_f32_e32 v12, v12
	v_pk_mul_f32 v[14:15], v[24:25], v[46:47] op_sel_hi:[1,0]
	v_add_f32_e32 v13, 1.0, v13
	v_rcp_f32_e32 v13, v13
	v_pk_mul_f32 v[6:7], v[6:7], v[14:15]
	v_lshlrev_b32_e32 v14, 16, v2
	v_mul_f32_e32 v15, 0xbfb8aa3b, v14
	v_exp_f32_e32 v16, v15
	v_pk_mul_f32 v[0:1], v[12:13], v[0:1]
	v_and_b32_e32 v15, 0xffff0000, v2
	v_pk_mul_f32 v[6:7], v[0:1], v[6:7]
	v_mul_f32_e32 v1, 0xbfb8aa3b, v15
	v_exp_f32_e32 v1, v1
	v_pk_mul_f32 v[12:13], v[22:23], v[46:47] op_sel_hi:[1,0]
	v_lshlrev_b32_e32 v2, 16, v3
	v_and_b32_e32 v3, 0xffff0000, v3
	s_waitcnt vmcnt(0)
	v_pk_mul_f32 v[8:9], v[8:9], v[12:13]
	v_mul_f32_e32 v12, 0xbfb8aa3b, v2
	v_mul_f32_e32 v13, 0xbfb8aa3b, v3
	v_exp_f32_e32 v12, v12
	v_exp_f32_e32 v13, v13
	v_add_f32_e32 v0, 1.0, v16
	v_add_f32_e32 v1, 1.0, v1
	v_rcp_f32_e32 v0, v0
	v_rcp_f32_e32 v1, v1
	v_add_f32_e32 v12, 1.0, v12
	v_add_f32_e32 v13, 1.0, v13
	v_rcp_f32_e32 v12, v12
	v_rcp_f32_e32 v13, v13
	v_pk_mul_f32 v[0:1], v[0:1], v[14:15]
	v_pk_mul_f32 v[2:3], v[12:13], v[2:3]
	v_pk_mul_f32 v[8:9], v[0:1], v[8:9]
	v_pk_mul_f32 v[0:1], v[20:21], v[46:47] op_sel_hi:[1,0]
	s_nop 0
	v_pk_mul_f32 v[0:1], v[10:11], v[0:1]
	s_nop 0
	v_pk_mul_f32 v[10:11], v[2:3], v[0:1]
	v_cvt_pk_bf16_f32 v0, v4, v5
	v_cvt_pk_bf16_f32 v1, v6, v7
	v_cvt_pk_bf16_f32 v2, v8, v9
	v_cvt_pk_bf16_f32 v3, v10, v11
	global_store_dwordx4 v[32:33], v[0:3], off offset:48
	s_barrier
; __device__ __forceinline__ float bf2f(unsigned b) { return __uint_as_float(b << 16); }
; __device__ __forceinline__ float quad_sum(float v) { v += dppf<0xB1>(v); v += dppf<0x4E>(v); return v; }
; __device__ __forceinline__ void ret_sample_unit(PR P, LAS float* lds, const int b, const int h, const int wv) {
;     ...
;     const float lg2 = log2f(1.0f - exp2f(-5.0f - (float)h));
;     const int row0 = MP + b * 4;
;     { const int t = (tid & 255) >> 6, f = tid & 63; const bf16_t* src = PS + (size_t)(row0 + t) * NCOLS + 1792 + h * 128;
;       if (tid < 256) { const float cs = rc[(2048 + t) * 64 + f], sn = rs[(2048 + t) * 64 + f];
;           const float q1 = bf2f(src[f]), q2 = bf2f(src[f + 64]); q[t * 128 + f] = q1 * cs - q2 * sn; q[t * 128 + f + 64] = q1 * sn + q2 * cs;
;           const float k1 = bf2f(src[512 + f]), k2 = bf2f(src[512 + f + 64]); k[t * 128 + f] = (k1 * cs - k2 * sn) * 0.08838834764831845f; k[t * 128 + f + 64] = (k1 * sn + k2 * cs) * 0.08838834764831845f; }
;       else { v[t * 128 + f] = bf2f(src[1024 + f]); v[t * 128 + f + 64] = bf2f(src[1024 + f + 64]); } }
;     __syncthreads();
;     if (wid == 0) { const int pi = lane >> 4, pj = (lane >> 2) & 3, part = lane & 3; float s = 0.f;
;         for (int d = part * 32; d < part * 32 + 32; ++d) s += q[pi * 128 + d] * k[pj * 128 + d];
;         s = quad_sum(s); if (part == 0) Pm[pi * 4 + pj] = pi >= pj ? s * exp2f(lg2 * (float)(pi - pj)) : 0.f; }
;     { const int e = tid & 127, dg = tid >> 7; const float c4 = exp2f(lg2 * 4.0f), g3 = exp2f(lg2 * 3.0f), g2_ = exp2f(lg2 * 2.0f), g1 = exp2f(lg2);
; __global__ void __launch_bounds__(512, 2) hymba_mega(Params P_unused) {
;     ...
;         for (int u = ob; u < 2560; u += 128) { if (u < 2048) rwkv_unit<true>(P, ldsf, u >> 4, (u >> 1) & 7, u & 1, wv); else ret_sample_unit(P, ldsf, (u - 2048) >> 2, (u - 2048) & 3, wv); }
	s_cbranch_scc0 .LBB0_654
	s_cmpk_gt_i32 s2, 0xa7f
	s_cbranch_scc1 .LBB0_689
	s_add_u32 s18, s10, 0x3d44800
	s_addc_u32 s19, s11, 0
	s_add_u32 s6, s8, 0x5588000
	s_addc_u32 s7, s9, 0
	s_add_u32 s20, s10, 0xea84800
	s_addc_u32 s21, s11, 0
	s_add_u32 s22, s10, 0xda04800
	s_addc_u32 s23, s11, 0
	s_add_u32 s24, s10, 0xbae4800
	s_addc_u32 s25, s11, 0
	s_add_u32 s26, s8, 0x4588000
	s_addc_u32 s27, s9, 0
	s_and_b32 s44, s2, 3
	v_cvt_f32_ubyte0_e32 v0, s44
	v_sub_f32_e32 v0, 0xc0a00000, v0
	s_mov_b32 s45, 0xc2fc0000
	v_mov_b32_e32 v72, 0x42800000
	v_cmp_gt_f32_e32 vcc, s45, v0
	s_and_b64 s[8:9], vcc, exec
	s_cselect_b32 s8, 0xffffffc0, 0
	v_cndmask_b32_e32 v1, 0, v72, vcc
	v_add_f32_e32 v0, v0, v1
	v_exp_f32_e32 v0, v0
	s_mov_b32 s46, 0x800000
	v_mov_b32_e32 v1, 0x42000000
	s_mov_b32 s29, 0
	v_ldexp_f32 v0, v0, s8
	v_sub_f32_e32 v0, 1.0, v0
	v_cmp_gt_f32_e32 vcc, s46, v0
	s_and_b64 s[8:9], vcc, exec
	s_cselect_b32 s8, 32, 0
	v_ldexp_f32 v0, v0, s8
	v_log_f32_e32 v0, v0
	v_cndmask_b32_e32 v1, 0, v1, vcc
	s_lshl_b32 s47, s44, 7
	s_movk_i32 s57, 0xf00
	v_sub_f32_e32 v73, v0, v1
	v_add_f32_e32 v2, v73, v73
	v_cmp_gt_f32_e32 vcc, s45, v2
	v_mul_f32_e32 v0, 4.0, v73
	s_and_b64 s[8:9], vcc, exec
	v_cndmask_b32_e32 v2, 0, v72, vcc
	v_fmac_f32_e32 v2, 2.0, v73
	v_cmp_gt_f32_e32 vcc, s45, v0
	v_exp_f32_e32 v2, v2
	s_cselect_b32 s8, 0xffffffc0, 0
	v_cndmask_b32_e32 v0, 0, v72, vcc
	v_fmac_f32_e32 v0, 4.0, v73
	v_exp_f32_e32 v0, v0
	v_mul_f32_e32 v1, 0x40400000, v73
	v_ldexp_f32 v74, v2, s8
	s_and_b64 s[8:9], vcc, exec
	s_cselect_b32 s8, 0xffffffc0, 0
	v_cmp_gt_f32_e32 vcc, s45, v1
	v_ldexp_f32 v75, v0, s8
	s_and_b64 s[8:9], vcc, exec
	v_cndmask_b32_e32 v0, 0, v72, vcc
	v_fmac_f32_e32 v0, 0x40400000, v73
	v_cmp_gt_f32_e32 vcc, s45, v73
	v_exp_f32_e32 v0, v0
	s_cselect_b32 s8, 0xffffffc0, 0
	v_cndmask_b32_e32 v1, 0, v72, vcc
	v_add_f32_e32 v1, v73, v1
	v_exp_f32_e32 v1, v1
	v_ldexp_f32 v76, v0, s8
	s_and_b64 s[8:9], vcc, exec
	s_cselect_b32 s8, 0xffffffc0, 0
	v_ldexp_f32 v77, v1, s8
	s_lshl_b32 s8, s44, 8
	s_add_u32 s30, s4, s8
	s_addc_u32 s31, s5, 0
	s_add_u32 s34, s18, s8
	s_addc_u32 s35, s19, 0
	s_lshr_b32 s8, s49, 4
	s_add_i32 s4, s8, 0x4200
	s_lshl_b32 s5, s8, 9
	s_lshl_b32 s9, s2, 5
	s_lshl_b32 s8, s8, 2
	s_add_i32 s55, s9, 0xfffff000
	s_add_i32 s56, s8, 0x4010
	v_mov_b32_e32 v25, 0
	s_movk_i32 s60, 0xff
	s_mov_b64 s[36:37], 0xe00
	s_movk_i32 s61, 0xff90
	s_movk_i32 s62, 0x1e00
	s_movk_i32 s63, 0x1000
	v_mov_b32_e32 v78, 0x3727c5ac
	s_movk_i32 s64, 0x7fff
	s_movk_i32 s65, 0x600
	v_mov_b32_e32 v79, 0x80000
	v_not_b32_e32 v80, 63
	v_mov_b32_e32 v81, 0xffffe000
	s_branch .LBB0_659
